# code placement: one 4-byte pad at the out-proj phase entry so that all four GEMM K-loop heads (and the attention fast path) start at 0 mod 8 bytes
# speedup vs baseline: 1.0092x; 1.0092x over previous
; __global__ void __launch_bounds__(NTHR, 2) mk_fwd(Args a_by_value) {
;     ...
;         else if (p == 5) {
;             PHASE_ENTER(5);
;             pg8::Gemm g{(const bf16_t*)(R + R_Y), (const bf16_t*)(ws + WS_WOUT), DM}; pg8::Order S; S.init(MT, DM, G, bx, 1, DM / 64);
;             EpiRes E{l == 0 ? a.in[I_X] : a.out, a.out, (bf16_t*)(ws + WS_XB), (float*)(ws + WS_SSQ)};
;             pg8::gemm_phase(ldsl, g, S, E, tid);
.LBB0_40:
	s_and_b64 vcc, exec, s[4:5]
	s_cbranch_vccz .LBB0_118
	s_cmp_gt_i32 s47, 4
	s_mov_b64 s[4:5], -1
	s_cbranch_scc0 .LBB0_85
	s_mov_b32 s6, s3
	s_mov_b32 s10, s2
	s_mov_b64 s[4:5], s[0:1]
	s_mov_b32 s7, s46
	s_waitcnt lgkmcnt(0)
	s_mov_b32 s28, s37
	v_mbcnt_lo_u32_b32 v11, -1, 0
	v_mbcnt_hi_u32_b32 v11, -1, v11
	v_lshl_or_b32 v11, s6, 6, v11
	s_nop 0
	s_cmp_eq_u32 s7, 0
	s_cselect_b32 s6, 0, 0xa8
	s_add_u32 s18, s4, s6
	s_addc_u32 s19, s5, 0
	s_cmpk_lt_i32 s10, 0x200
	s_cselect_b64 s[6:7], -1, 0
	s_cmpk_gt_i32 s10, 0x1ff
	v_readfirstlane_b32 s50, v11
	s_cbranch_scc1 .LBB0_48
	s_ashr_i32 s11, s10, 31
	s_lshr_b32 s11, s11, 29
	s_add_i32 s11, s10, s11
	s_and_b32 s12, s11, -8
	s_sub_i32 s14, s10, s12
	s_cmp_gt_i32 s14, -1
	s_mov_b64 s[12:13], -1
	s_cbranch_scc0 .LBB0_45
	s_lshl_b32 s15, s14, 6
	s_mov_b64 s[12:13], 0
